# P0: silu inputs loaded up front; adaLN GEMV keeps 32 weight rows in flight (on top of fused final norm)
# speedup vs baseline: 1.0036x; 1.0036x over previous
; #define LAS __attribute__((address_space(3)))
; __device__ __forceinline__ void p0_prologue(const Args& A, LAS unsigned char* lds, int tid, int lane, int wave) {
;     ...
;     {
;         LAS float* sc = (LAS float*)lds; LAS float* red = (LAS float*)(lds + 16384);
;         for (int i = tid; i < BATCH * DM; i += 512) { const float v = A.c[i]; sc[i] = v / (1.f + expf(-v)); }
;         __syncthreads();
;         for (int item = blockIdx.x; item < NMODC / 64; item += gridDim.x) {
;             const float* wp = A.w_ada + (size_t)(wave * 128) * NMODC + item * 64 + lane;
;             float a0 = 0.f, a1 = 0.f, a2 = 0.f, a3 = 0.f;
; #pragma unroll 8
;             for (int k = 0; k < 128; ++k) { const float w = wp[(size_t)k * NMODC]; const int kk = wave * 128 + k;
.LBB0_7:
	v_readlane_b32 s0, v254, 0
	s_lshr_b32 s0, s0, 6
	s_cmp_lt_i32 s48, 1
	v_writelane_b32 v254, s0, 7
	s_cselect_b64 s[0:1], -1, 0
	s_cmp_gt_i32 s49, 0
	s_cselect_b64 s[2:3], -1, 0
	s_and_b64 s[8:9], s[0:1], s[2:3]
	s_andn2_b64 vcc, exec, s[8:9]
	v_and_b32_e32 v220, 63, v0
	s_cbranch_vccnz .LBB0_87
	v_readlane_b32 s0, v254, 1
	v_readlane_b32 s1, v254, 2
	s_load_dwordx2 s[10:11], s[0:1], 0x98
	s_nop 0
	s_load_dwordx2 s[0:1], s[0:1], 0x8
	v_lshlrev_b32_e32 v2, 2, v0
	v_mov_b32_e32 v3, 0
	v_or_b32_e32 v1, 0xfffffe00, v0
	v_add_u32_e32 v4, 0, v2
	s_waitcnt lgkmcnt(0)
	v_add_u32_e32 v240, 0x1000, v2
	v_add_u32_e32 v241, 0x2000, v2
	v_add_u32_e32 v242, 0x3000, v2
	global_load_dword v232, v2, s[0:1]
	global_load_dword v233, v2, s[0:1] offset:2048
	global_load_dword v234, v240, s[0:1]
	global_load_dword v235, v240, s[0:1] offset:2048
	global_load_dword v236, v241, s[0:1]
	global_load_dword v237, v241, s[0:1] offset:2048
	global_load_dword v238, v242, s[0:1]
	global_load_dword v239, v242, s[0:1] offset:2048
	s_waitcnt vmcnt(0)
	ds_write_b32 v4, v232
	ds_write_b32 v4, v233 offset:2048
	ds_write_b32 v4, v234 offset:4096
	ds_write_b32 v4, v235 offset:6144
	ds_write_b32 v4, v236 offset:8192
	ds_write_b32 v4, v237 offset:10240
	ds_write_b32 v4, v238 offset:12288
	ds_write_b32 v4, v239 offset:14336
	s_waitcnt lgkmcnt(0)
	v_lshl_add_u64 v[2:3], s[0:1], 0, v[2:3]
	s_mov_b64 s[0:1], 0
	s_mov_b32 s4, 0xbfb8aa3b
	s_mov_b32 s5, 0x42ce8ed0
	s_mov_b32 s6, 0xc2b17218
	v_mov_b32_e32 v5, 0x7f800000
	s_mov_b64 s[2:3], 0x800
	s_movk_i32 s7, 0xdff
.LBB0_9:
	ds_read_b32 v6, v4
	v_add_u32_e32 v1, 0x200, v1
	v_cmp_lt_u32_e32 vcc, s7, v1
	s_or_b64 s[0:1], vcc, s[0:1]
	v_lshl_add_u64 v[2:3], v[2:3], 0, s[2:3]
	s_waitcnt lgkmcnt(0)
	v_mul_f32_e32 v7, 0xbfb8aa3b, v6
	v_rndne_f32_e32 v8, v7
	v_fma_f32 v9, v6, s4, -v7
	v_sub_f32_e32 v7, v7, v8
	v_fmac_f32_e32 v9, 0xb2a5705f, v6
	v_add_f32_e32 v7, v7, v9
	v_cvt_i32_f32_e32 v8, v8
	v_exp_f32_e32 v7, v7
	v_cmp_nlt_f32_e32 vcc, s5, v6
	v_ldexp_f32 v7, v7, v8
	s_nop 0
	v_cndmask_b32_e32 v7, 0, v7, vcc
	v_cmp_ngt_f32_e32 vcc, s6, v6
	s_nop 1
	v_cndmask_b32_e32 v7, v5, v7, vcc
	v_add_f32_e32 v7, 1.0, v7
	v_div_scale_f32 v8, s[12:13], v7, v7, v6
	v_rcp_f32_e32 v9, v8
	v_div_scale_f32 v10, vcc, v6, v7, v6
	v_fma_f32 v11, -v8, v9, 1.0
	v_fmac_f32_e32 v9, v11, v9
	v_mul_f32_e32 v11, v10, v9
	v_fma_f32 v12, -v8, v11, v10
	v_fmac_f32_e32 v11, v12, v9
	v_fma_f32 v8, -v8, v11, v10
	v_div_fmas_f32 v8, v8, v9, v11
	v_div_fixup_f32 v6, v8, v7, v6
	ds_write_b32 v4, v6
	v_add_u32_e32 v4, 0x800, v4
	s_andn2_b64 exec, exec, s[0:1]
	s_cbranch_execnz .LBB0_9
	s_or_b64 exec, exec, s[0:1]
	s_cmpk_gt_i32 s87, 0x8f
	s_waitcnt lgkmcnt(0)
	s_barrier
	s_cbranch_scc1 .LBB0_17
	v_readlane_b32 s1, v254, 7
	s_lshl_b32 s0, s1, 7
	s_mul_hi_u32 s5, s0, 0x9000
	s_lshl_b32 s0, s1, 9
	v_readlane_b32 s6, v254, 1
	s_add_i32 s13, s0, 0
	s_movk_i32 s0, 0x100
	v_readlane_b32 s7, v254, 2
	s_mul_i32 s4, s1, 0x480000
	s_lshl_b32 s14, s1, 10
	v_cmp_gt_u32_e32 vcc, s0, v0
	s_load_dwordx4 s[0:3], s[6:7], 0x10
	v_lshlrev_b32_e32 v6, 2, v220
	v_lshrrev_b32_e32 v2, 6, v0
	v_add_u32_e32 v1, 0, v6
	v_and_b32_e32 v3, 0xc0, v0
	v_mul_u32_u24_e32 v2, 0x2400, v2
	v_lshl_add_u32 v14, v3, 2, v1
	v_lshlrev_b32_e32 v2, 2, v2
	v_mov_b32_e32 v3, 0
	s_waitcnt lgkmcnt(0)
	s_add_u32 s0, s0, s4
	v_lshl_add_u64 v[4:5], s[10:11], 0, v[2:3]
	v_mov_b32_e32 v7, v3
	s_addc_u32 s1, s1, s5
	s_mov_b32 s12, 0x9000
	v_lshl_add_u64 v[4:5], v[4:5], 0, v[6:7]
	v_lshl_add_u64 v[6:7], s[0:1], 0, v[6:7]
	s_lshl_b32 s4, s87, 6
	s_lshl_b32 s15, s33, 6
	s_mov_b32 s16, 0x12000
	s_mov_b32 s17, 0x1b000
	s_mov_b32 s18, 0x24000
	s_mov_b32 s19, 0x2d000
	s_mov_b32 s20, 0x36000
	s_mov_b32 s21, 0x3f000
	s_mov_b32 s22, s87
	s_branch .LBB0_13

; __device__ __forceinline__ void p0_prologue(const Args& A, LAS unsigned char* lds, int tid, int lane, int wave) {
;     ...
;             const float* wp = A.w_ada + (size_t)(wave * 128) * NMODC + item * 64 + lane;
;             float a0 = 0.f, a1 = 0.f, a2 = 0.f, a3 = 0.f;
; #pragma unroll 8
;             for (int k = 0; k < 128; ++k) { const float w = wp[(size_t)k * NMODC]; const int kk = wave * 128 + k;
;                 a0 += sc[kk] * w; a1 += sc[DM + kk] * w; a2 += sc[2 * DM + kk] * w; a3 += sc[3 * DM + kk] * w; }
.LBB0_14:
	s_mov_b32 s0, s6
	s_mov_b32 s1, s7
	v_lshl_add_u64 v[16:17], v[8:9], 0, s[0:1]
	global_load_dword v100, v[16:17], off
	s_add_u32 s0, s0, 0x9000
	s_addc_u32 s1, s1, 0
	v_lshl_add_u64 v[16:17], v[8:9], 0, s[0:1]
	global_load_dword v102, v[16:17], off
	s_add_u32 s0, s0, 0x9000
	s_addc_u32 s1, s1, 0
	v_lshl_add_u64 v[16:17], v[8:9], 0, s[0:1]
	global_load_dword v104, v[16:17], off
	s_add_u32 s0, s0, 0x9000
	s_addc_u32 s1, s1, 0
	v_lshl_add_u64 v[16:17], v[8:9], 0, s[0:1]
	global_load_dword v106, v[16:17], off
	s_add_u32 s0, s0, 0x9000
	s_addc_u32 s1, s1, 0
	v_lshl_add_u64 v[16:17], v[8:9], 0, s[0:1]
	global_load_dword v108, v[16:17], off
	s_add_u32 s0, s0, 0x9000
	s_addc_u32 s1, s1, 0
	v_lshl_add_u64 v[16:17], v[8:9], 0, s[0:1]
	global_load_dword v110, v[16:17], off
	s_add_u32 s0, s0, 0x9000
	s_addc_u32 s1, s1, 0
	v_lshl_add_u64 v[16:17], v[8:9], 0, s[0:1]
	global_load_dword v112, v[16:17], off
	s_add_u32 s0, s0, 0x9000
	s_addc_u32 s1, s1, 0
	v_lshl_add_u64 v[16:17], v[8:9], 0, s[0:1]
	global_load_dword v114, v[16:17], off
	s_add_u32 s0, s0, 0x9000
	s_addc_u32 s1, s1, 0
	v_lshl_add_u64 v[16:17], v[8:9], 0, s[0:1]
	global_load_dword v116, v[16:17], off
	s_add_u32 s0, s0, 0x9000
	s_addc_u32 s1, s1, 0
	v_lshl_add_u64 v[16:17], v[8:9], 0, s[0:1]
	global_load_dword v118, v[16:17], off
	s_add_u32 s0, s0, 0x9000
	s_addc_u32 s1, s1, 0
	v_lshl_add_u64 v[16:17], v[8:9], 0, s[0:1]
	global_load_dword v120, v[16:17], off
	s_add_u32 s0, s0, 0x9000
	s_addc_u32 s1, s1, 0
	v_lshl_add_u64 v[16:17], v[8:9], 0, s[0:1]
	global_load_dword v122, v[16:17], off
	s_add_u32 s0, s0, 0x9000
	s_addc_u32 s1, s1, 0
	v_lshl_add_u64 v[16:17], v[8:9], 0, s[0:1]
	global_load_dword v124, v[16:17], off
	s_add_u32 s0, s0, 0x9000
	s_addc_u32 s1, s1, 0
	v_lshl_add_u64 v[16:17], v[8:9], 0, s[0:1]
	global_load_dword v126, v[16:17], off
	s_add_u32 s0, s0, 0x9000
	s_addc_u32 s1, s1, 0
	v_lshl_add_u64 v[16:17], v[8:9], 0, s[0:1]
	global_load_dword v128, v[16:17], off
	s_add_u32 s0, s0, 0x9000
	s_addc_u32 s1, s1, 0
	v_lshl_add_u64 v[16:17], v[8:9], 0, s[0:1]
	global_load_dword v130, v[16:17], off
	s_add_u32 s0, s0, 0x9000
	s_addc_u32 s1, s1, 0
	v_lshl_add_u64 v[16:17], v[8:9], 0, s[0:1]
	global_load_dword v132, v[16:17], off
	s_add_u32 s0, s0, 0x9000
	s_addc_u32 s1, s1, 0
	v_lshl_add_u64 v[16:17], v[8:9], 0, s[0:1]
	global_load_dword v134, v[16:17], off
	s_add_u32 s0, s0, 0x9000
	s_addc_u32 s1, s1, 0
	v_lshl_add_u64 v[16:17], v[8:9], 0, s[0:1]
	global_load_dword v136, v[16:17], off
	s_add_u32 s0, s0, 0x9000
	s_addc_u32 s1, s1, 0
	v_lshl_add_u64 v[16:17], v[8:9], 0, s[0:1]
	global_load_dword v138, v[16:17], off
	s_add_u32 s0, s0, 0x9000
	s_addc_u32 s1, s1, 0
	v_lshl_add_u64 v[16:17], v[8:9], 0, s[0:1]
	global_load_dword v140, v[16:17], off
	s_add_u32 s0, s0, 0x9000
	s_addc_u32 s1, s1, 0
	v_lshl_add_u64 v[16:17], v[8:9], 0, s[0:1]
	global_load_dword v142, v[16:17], off
	s_add_u32 s0, s0, 0x9000
	s_addc_u32 s1, s1, 0
	v_lshl_add_u64 v[16:17], v[8:9], 0, s[0:1]
	global_load_dword v144, v[16:17], off
	s_add_u32 s0, s0, 0x9000
	s_addc_u32 s1, s1, 0
	v_lshl_add_u64 v[16:17], v[8:9], 0, s[0:1]
	global_load_dword v146, v[16:17], off
	s_add_u32 s0, s0, 0x9000
	s_addc_u32 s1, s1, 0
	v_lshl_add_u64 v[16:17], v[8:9], 0, s[0:1]
	global_load_dword v148, v[16:17], off
	s_add_u32 s0, s0, 0x9000
	s_addc_u32 s1, s1, 0
	v_lshl_add_u64 v[16:17], v[8:9], 0, s[0:1]
	global_load_dword v150, v[16:17], off
	s_add_u32 s0, s0, 0x9000
	s_addc_u32 s1, s1, 0
	v_lshl_add_u64 v[16:17], v[8:9], 0, s[0:1]
	global_load_dword v152, v[16:17], off
	s_add_u32 s0, s0, 0x9000
	s_addc_u32 s1, s1, 0
	v_lshl_add_u64 v[16:17], v[8:9], 0, s[0:1]
	global_load_dword v154, v[16:17], off
	s_add_u32 s0, s0, 0x9000
	s_addc_u32 s1, s1, 0
	v_lshl_add_u64 v[16:17], v[8:9], 0, s[0:1]
	global_load_dword v156, v[16:17], off
	s_add_u32 s0, s0, 0x9000
	s_addc_u32 s1, s1, 0
	v_lshl_add_u64 v[16:17], v[8:9], 0, s[0:1]
	global_load_dword v158, v[16:17], off
	s_add_u32 s0, s0, 0x9000
	s_addc_u32 s1, s1, 0
	v_lshl_add_u64 v[16:17], v[8:9], 0, s[0:1]
	global_load_dword v160, v[16:17], off
	s_add_u32 s0, s0, 0x9000
	s_addc_u32 s1, s1, 0
	v_lshl_add_u64 v[16:17], v[8:9], 0, s[0:1]
	global_load_dword v162, v[16:17], off
	s_add_u32 s6, s6, 0x120000
	s_addc_u32 s7, s7, 0
	v_mov_b32_e32 v15, s5
	s_add_i32 s5, s5, 32
	ds_read_b128 v[16:19], v15
	ds_read_b128 v[20:23], v15 offset:16
	ds_read_b128 v[24:27], v15 offset:4096
	ds_read_b128 v[28:31], v15 offset:4112
	ds_read_b128 v[32:35], v15 offset:8192
	ds_read_b128 v[36:39], v15 offset:8208
	ds_read_b128 v[40:43], v15 offset:12288
	ds_read_b128 v[44:47], v15 offset:12304
	s_waitcnt lgkmcnt(7)
	v_mov_b32_e32 v62, v16
	s_waitcnt lgkmcnt(5)
	v_mov_b32_e32 v63, v24
	s_waitcnt lgkmcnt(3)
	v_mov_b32_e32 v64, v32
	s_waitcnt lgkmcnt(1)
	v_mov_b32_e32 v65, v40
	v_mov_b32_e32 v24, v17
	v_mov_b32_e32 v40, v33
	v_mov_b32_e32 v16, v18
	v_mov_b32_e32 v17, v26
	v_mov_b32_e32 v26, v19
	v_mov_b32_e32 v18, v34
	v_mov_b32_e32 v19, v42
	v_mov_b32_e32 v42, v35
	v_mov_b32_e32 v32, v20
	v_mov_b32_e32 v33, v28
	v_mov_b32_e32 v34, v36
	s_waitcnt lgkmcnt(0)
	v_mov_b32_e32 v35, v44
	v_mov_b32_e32 v28, v21
	v_mov_b32_e32 v44, v37
	v_mov_b32_e32 v20, v22
	v_mov_b32_e32 v21, v30
	v_mov_b32_e32 v30, v23
	v_mov_b32_e32 v22, v38
	v_mov_b32_e32 v23, v46
	v_mov_b32_e32 v46, v39
	s_waitcnt vmcnt(31)
	v_pk_fma_f32 v[10:11], v[100:101], v[62:63], v[10:11] op_sel_hi:[0,1,1]
	v_pk_fma_f32 v[12:13], v[100:101], v[64:65], v[12:13] op_sel_hi:[0,1,1]
	s_waitcnt vmcnt(30)
	v_pk_fma_f32 v[10:11], v[102:103], v[24:25], v[10:11] op_sel_hi:[0,1,1]
	v_pk_fma_f32 v[12:13], v[102:103], v[40:41], v[12:13] op_sel_hi:[0,1,1]
	s_waitcnt vmcnt(29)
; __device__ __forceinline__ void p0_prologue(const Args& A, LAS unsigned char* lds, int tid, int lane, int wave) {
;     ...
;             const float* wp = A.w_ada + (size_t)(wave * 128) * NMODC + item * 64 + lane;
;             float a0 = 0.f, a1 = 0.f, a2 = 0.f, a3 = 0.f;
; #pragma unroll 8
;             for (int k = 0; k < 128; ++k) { const float w = wp[(size_t)k * NMODC]; const int kk = wave * 128 + k;
;                 a0 += sc[kk] * w; a1 += sc[DM + kk] * w; a2 += sc[2 * DM + kk] * w; a3 += sc[3 * DM + kk] * w; }
	v_pk_fma_f32 v[10:11], v[104:105], v[16:17], v[10:11] op_sel_hi:[0,1,1]
	v_pk_fma_f32 v[12:13], v[104:105], v[18:19], v[12:13] op_sel_hi:[0,1,1]
	s_waitcnt vmcnt(28)
	v_pk_fma_f32 v[10:11], v[106:107], v[26:27], v[10:11] op_sel_hi:[0,1,1]
	v_pk_fma_f32 v[12:13], v[106:107], v[42:43], v[12:13] op_sel_hi:[0,1,1]
	s_waitcnt vmcnt(27)
	v_pk_fma_f32 v[10:11], v[108:109], v[32:33], v[10:11] op_sel_hi:[0,1,1]
	v_pk_fma_f32 v[12:13], v[108:109], v[34:35], v[12:13] op_sel_hi:[0,1,1]
	s_waitcnt vmcnt(26)
	v_pk_fma_f32 v[10:11], v[110:111], v[28:29], v[10:11] op_sel_hi:[0,1,1]
	v_pk_fma_f32 v[12:13], v[110:111], v[44:45], v[12:13] op_sel_hi:[0,1,1]
	s_waitcnt vmcnt(25)
	v_pk_fma_f32 v[10:11], v[112:113], v[20:21], v[10:11] op_sel_hi:[0,1,1]
	v_pk_fma_f32 v[12:13], v[112:113], v[22:23], v[12:13] op_sel_hi:[0,1,1]
	s_waitcnt vmcnt(24)
	v_pk_fma_f32 v[10:11], v[114:115], v[30:31], v[10:11] op_sel_hi:[0,1,1]
	v_pk_fma_f32 v[12:13], v[114:115], v[46:47], v[12:13] op_sel_hi:[0,1,1]
	v_mov_b32_e32 v15, s5
	s_add_i32 s5, s5, 32
	ds_read_b128 v[16:19], v15
	ds_read_b128 v[20:23], v15 offset:16
	ds_read_b128 v[24:27], v15 offset:4096
	ds_read_b128 v[28:31], v15 offset:4112
	ds_read_b128 v[32:35], v15 offset:8192
	ds_read_b128 v[36:39], v15 offset:8208
	ds_read_b128 v[40:43], v15 offset:12288
	ds_read_b128 v[44:47], v15 offset:12304
	s_waitcnt lgkmcnt(7)
	v_mov_b32_e32 v62, v16
	s_waitcnt lgkmcnt(5)
	v_mov_b32_e32 v63, v24
	s_waitcnt lgkmcnt(3)
	v_mov_b32_e32 v64, v32
	s_waitcnt lgkmcnt(1)
	v_mov_b32_e32 v65, v40
	v_mov_b32_e32 v24, v17
	v_mov_b32_e32 v40, v33
	v_mov_b32_e32 v16, v18
	v_mov_b32_e32 v17, v26
	v_mov_b32_e32 v26, v19
	v_mov_b32_e32 v18, v34
	v_mov_b32_e32 v19, v42
	v_mov_b32_e32 v42, v35
	v_mov_b32_e32 v32, v20
	v_mov_b32_e32 v33, v28
	v_mov_b32_e32 v34, v36
	s_waitcnt lgkmcnt(0)
	v_mov_b32_e32 v35, v44
	v_mov_b32_e32 v28, v21
	v_mov_b32_e32 v44, v37
	v_mov_b32_e32 v20, v22
	v_mov_b32_e32 v21, v30
	v_mov_b32_e32 v30, v23
	v_mov_b32_e32 v22, v38
	v_mov_b32_e32 v23, v46
	v_mov_b32_e32 v46, v39
	s_waitcnt vmcnt(23)
	v_pk_fma_f32 v[10:11], v[116:117], v[62:63], v[10:11] op_sel_hi:[0,1,1]
	v_pk_fma_f32 v[12:13], v[116:117], v[64:65], v[12:13] op_sel_hi:[0,1,1]
	s_waitcnt vmcnt(22)
	v_pk_fma_f32 v[10:11], v[118:119], v[24:25], v[10:11] op_sel_hi:[0,1,1]
	v_pk_fma_f32 v[12:13], v[118:119], v[40:41], v[12:13] op_sel_hi:[0,1,1]
	s_waitcnt vmcnt(21)
	v_pk_fma_f32 v[10:11], v[120:121], v[16:17], v[10:11] op_sel_hi:[0,1,1]
	v_pk_fma_f32 v[12:13], v[120:121], v[18:19], v[12:13] op_sel_hi:[0,1,1]
	s_waitcnt vmcnt(20)
	v_pk_fma_f32 v[10:11], v[122:123], v[26:27], v[10:11] op_sel_hi:[0,1,1]
	v_pk_fma_f32 v[12:13], v[122:123], v[42:43], v[12:13] op_sel_hi:[0,1,1]
	s_waitcnt vmcnt(19)
	v_pk_fma_f32 v[10:11], v[124:125], v[32:33], v[10:11] op_sel_hi:[0,1,1]
	v_pk_fma_f32 v[12:13], v[124:125], v[34:35], v[12:13] op_sel_hi:[0,1,1]
	s_waitcnt vmcnt(18)
	v_pk_fma_f32 v[10:11], v[126:127], v[28:29], v[10:11] op_sel_hi:[0,1,1]
	v_pk_fma_f32 v[12:13], v[126:127], v[44:45], v[12:13] op_sel_hi:[0,1,1]
	s_waitcnt vmcnt(17)
	v_pk_fma_f32 v[10:11], v[128:129], v[20:21], v[10:11] op_sel_hi:[0,1,1]
	v_pk_fma_f32 v[12:13], v[128:129], v[22:23], v[12:13] op_sel_hi:[0,1,1]
	s_waitcnt vmcnt(16)
	v_pk_fma_f32 v[10:11], v[130:131], v[30:31], v[10:11] op_sel_hi:[0,1,1]
	v_pk_fma_f32 v[12:13], v[130:131], v[46:47], v[12:13] op_sel_hi:[0,1,1]
	v_mov_b32_e32 v15, s5
	s_add_i32 s5, s5, 32
	ds_read_b128 v[16:19], v15
	ds_read_b128 v[20:23], v15 offset:16
	ds_read_b128 v[24:27], v15 offset:4096
	ds_read_b128 v[28:31], v15 offset:4112
	ds_read_b128 v[32:35], v15 offset:8192
	ds_read_b128 v[36:39], v15 offset:8208
	ds_read_b128 v[40:43], v15 offset:12288
	ds_read_b128 v[44:47], v15 offset:12304
	s_waitcnt lgkmcnt(7)
	v_mov_b32_e32 v62, v16
	s_waitcnt lgkmcnt(5)
	v_mov_b32_e32 v63, v24
	s_waitcnt lgkmcnt(3)
	v_mov_b32_e32 v64, v32
	s_waitcnt lgkmcnt(1)
	v_mov_b32_e32 v65, v40
	v_mov_b32_e32 v24, v17
	v_mov_b32_e32 v40, v33
	v_mov_b32_e32 v16, v18
	v_mov_b32_e32 v17, v26
	v_mov_b32_e32 v26, v19
	v_mov_b32_e32 v18, v34
	v_mov_b32_e32 v19, v42
	v_mov_b32_e32 v42, v35
	v_mov_b32_e32 v32, v20
	v_mov_b32_e32 v33, v28
	v_mov_b32_e32 v34, v36
	s_waitcnt lgkmcnt(0)
	v_mov_b32_e32 v35, v44
	v_mov_b32_e32 v28, v21
	v_mov_b32_e32 v44, v37
	v_mov_b32_e32 v20, v22
	v_mov_b32_e32 v21, v30
	v_mov_b32_e32 v30, v23
	v_mov_b32_e32 v22, v38
	v_mov_b32_e32 v23, v46
	v_mov_b32_e32 v46, v39
	s_waitcnt vmcnt(15)
	v_pk_fma_f32 v[10:11], v[132:133], v[62:63], v[10:11] op_sel_hi:[0,1,1]
	v_pk_fma_f32 v[12:13], v[132:133], v[64:65], v[12:13] op_sel_hi:[0,1,1]
	s_waitcnt vmcnt(14)
; __device__ __forceinline__ void p0_prologue(const Args& A, LAS unsigned char* lds, int tid, int lane, int wave) {
;     ...
; #pragma unroll 8
;             for (int k = 0; k < 128; ++k) { const float w = wp[(size_t)k * NMODC]; const int kk = wave * 128 + k;
;                 a0 += sc[kk] * w; a1 += sc[DM + kk] * w; a2 += sc[2 * DM + kk] * w; a3 += sc[3 * DM + kk] * w; }
;             red[(wave * 4 + 0) * 64 + lane] = a0; red[(wave * 4 + 1) * 64 + lane] = a1; red[(wave * 4 + 2) * 64 + lane] = a2; red[(wave * 4 + 3) * 64 + lane] = a3;
;             __syncthreads();
;             if (tid < 256) { const int b = tid >> 6, col = tid & 63; float s = A.b_ada[item * 64 + col];
; #pragma unroll
;                 for (int w = 0; w < 8; ++w) s += red[(w * 4 + b) * 64 + col];
;                 mods[(size_t)b * NMODC + item * 64 + col] = s; }
;             __syncthreads();
	v_pk_fma_f32 v[10:11], v[134:135], v[24:25], v[10:11] op_sel_hi:[0,1,1]
	v_pk_fma_f32 v[12:13], v[134:135], v[40:41], v[12:13] op_sel_hi:[0,1,1]
	s_waitcnt vmcnt(13)
	v_pk_fma_f32 v[10:11], v[136:137], v[16:17], v[10:11] op_sel_hi:[0,1,1]
	v_pk_fma_f32 v[12:13], v[136:137], v[18:19], v[12:13] op_sel_hi:[0,1,1]
	s_waitcnt vmcnt(12)
	v_pk_fma_f32 v[10:11], v[138:139], v[26:27], v[10:11] op_sel_hi:[0,1,1]
	v_pk_fma_f32 v[12:13], v[138:139], v[42:43], v[12:13] op_sel_hi:[0,1,1]
	s_waitcnt vmcnt(11)
	v_pk_fma_f32 v[10:11], v[140:141], v[32:33], v[10:11] op_sel_hi:[0,1,1]
	v_pk_fma_f32 v[12:13], v[140:141], v[34:35], v[12:13] op_sel_hi:[0,1,1]
	s_waitcnt vmcnt(10)
	v_pk_fma_f32 v[10:11], v[142:143], v[28:29], v[10:11] op_sel_hi:[0,1,1]
	v_pk_fma_f32 v[12:13], v[142:143], v[44:45], v[12:13] op_sel_hi:[0,1,1]
	s_waitcnt vmcnt(9)
	v_pk_fma_f32 v[10:11], v[144:145], v[20:21], v[10:11] op_sel_hi:[0,1,1]
	v_pk_fma_f32 v[12:13], v[144:145], v[22:23], v[12:13] op_sel_hi:[0,1,1]
	s_waitcnt vmcnt(8)
	v_pk_fma_f32 v[10:11], v[146:147], v[30:31], v[10:11] op_sel_hi:[0,1,1]
	v_pk_fma_f32 v[12:13], v[146:147], v[46:47], v[12:13] op_sel_hi:[0,1,1]
	v_mov_b32_e32 v15, s5
	s_add_i32 s5, s5, 32
	ds_read_b128 v[16:19], v15
	ds_read_b128 v[20:23], v15 offset:16
	ds_read_b128 v[24:27], v15 offset:4096
	ds_read_b128 v[28:31], v15 offset:4112
	ds_read_b128 v[32:35], v15 offset:8192
	ds_read_b128 v[36:39], v15 offset:8208
	ds_read_b128 v[40:43], v15 offset:12288
	ds_read_b128 v[44:47], v15 offset:12304
	s_waitcnt lgkmcnt(7)
	v_mov_b32_e32 v62, v16
	s_waitcnt lgkmcnt(5)
	v_mov_b32_e32 v63, v24
	s_waitcnt lgkmcnt(3)
	v_mov_b32_e32 v64, v32
	s_waitcnt lgkmcnt(1)
	v_mov_b32_e32 v65, v40
	v_mov_b32_e32 v24, v17
	v_mov_b32_e32 v40, v33
	v_mov_b32_e32 v16, v18
	v_mov_b32_e32 v17, v26
	v_mov_b32_e32 v26, v19
	v_mov_b32_e32 v18, v34
	v_mov_b32_e32 v19, v42
	v_mov_b32_e32 v42, v35
	v_mov_b32_e32 v32, v20
	v_mov_b32_e32 v33, v28
	v_mov_b32_e32 v34, v36
	s_waitcnt lgkmcnt(0)
	v_mov_b32_e32 v35, v44
	v_mov_b32_e32 v28, v21
	v_mov_b32_e32 v44, v37
	v_mov_b32_e32 v20, v22
	v_mov_b32_e32 v21, v30
	v_mov_b32_e32 v30, v23
	v_mov_b32_e32 v22, v38
	v_mov_b32_e32 v23, v46
	v_mov_b32_e32 v46, v39
	s_waitcnt vmcnt(7)
	v_pk_fma_f32 v[10:11], v[148:149], v[62:63], v[10:11] op_sel_hi:[0,1,1]
	v_pk_fma_f32 v[12:13], v[148:149], v[64:65], v[12:13] op_sel_hi:[0,1,1]
	s_waitcnt vmcnt(6)
	v_pk_fma_f32 v[10:11], v[150:151], v[24:25], v[10:11] op_sel_hi:[0,1,1]
	v_pk_fma_f32 v[12:13], v[150:151], v[40:41], v[12:13] op_sel_hi:[0,1,1]
	s_waitcnt vmcnt(5)
	v_pk_fma_f32 v[10:11], v[152:153], v[16:17], v[10:11] op_sel_hi:[0,1,1]
	v_pk_fma_f32 v[12:13], v[152:153], v[18:19], v[12:13] op_sel_hi:[0,1,1]
	s_waitcnt vmcnt(4)
	v_pk_fma_f32 v[10:11], v[154:155], v[26:27], v[10:11] op_sel_hi:[0,1,1]
	v_pk_fma_f32 v[12:13], v[154:155], v[42:43], v[12:13] op_sel_hi:[0,1,1]
	s_waitcnt vmcnt(3)
	v_pk_fma_f32 v[10:11], v[156:157], v[32:33], v[10:11] op_sel_hi:[0,1,1]
	v_pk_fma_f32 v[12:13], v[156:157], v[34:35], v[12:13] op_sel_hi:[0,1,1]
	s_waitcnt vmcnt(2)
	v_pk_fma_f32 v[10:11], v[158:159], v[28:29], v[10:11] op_sel_hi:[0,1,1]
	v_pk_fma_f32 v[12:13], v[158:159], v[44:45], v[12:13] op_sel_hi:[0,1,1]
	s_waitcnt vmcnt(1)
	v_pk_fma_f32 v[10:11], v[160:161], v[20:21], v[10:11] op_sel_hi:[0,1,1]
	v_pk_fma_f32 v[12:13], v[160:161], v[22:23], v[12:13] op_sel_hi:[0,1,1]
	s_waitcnt vmcnt(0)
	v_pk_fma_f32 v[10:11], v[162:163], v[30:31], v[10:11] op_sel_hi:[0,1,1]
	v_pk_fma_f32 v[12:13], v[162:163], v[46:47], v[12:13] op_sel_hi:[0,1,1]
	s_cmp_eq_u32 s6, 0x480000
	s_cbranch_scc0 .LBB0_14
	v_add_u32_e32 v2, s14, v1
	ds_write2st64_b32 v2, v10, v11 offset0:64 offset1:65
	ds_write2st64_b32 v2, v12, v13 offset0:66 offset1:67
	s_waitcnt lgkmcnt(0)
	s_barrier
	s_and_saveexec_b64 s[0:1], vcc
	s_cbranch_execz .LBB0_12
	s_lshl_b32 s6, s22, 6
	v_or_b32_e32 v8, s6, v220
	v_ashrrev_i32_e32 v9, 31, v8
	v_lshl_add_u64 v[8:9], v[8:9], 2, s[2:3]
	global_load_dword v2, v[8:9], off
	ds_read2st64_b32 v[8:9], v14 offset0:64 offset1:68
	ds_read2st64_b32 v[10:11], v14 offset0:72 offset1:76
	ds_read2st64_b32 v[12:13], v14 offset0:80 offset1:84
	ds_read2st64_b32 v[16:17], v14 offset0:88 offset1:92
	s_ashr_i32 s7, s6, 31
	s_waitcnt vmcnt(0) lgkmcnt(3)
	v_add_f32_e32 v2, v2, v8
	v_add_f32_e32 v2, v2, v9
	s_waitcnt lgkmcnt(2)
	v_add_f32_e32 v2, v2, v10
	v_add_f32_e32 v2, v2, v11
	s_waitcnt lgkmcnt(1)
	v_add_f32_e32 v2, v2, v12
	v_add_f32_e32 v2, v2, v13
	s_waitcnt lgkmcnt(0)
	v_add_f32_e32 v2, v2, v16
	v_add_f32_e32 v2, v2, v17
	v_lshl_add_u64 v[8:9], s[6:7], 2, v[4:5]
	global_store_dword v[8:9], v2, off
	s_branch .LBB0_12
